# gmlp: GU loads + wsp loads + rstd row loads de-serialised; attention bodies with deep LDS prefetch; XCD-aware attention unit order
# speedup vs baseline: 1.0330x; 1.0330x over previous
; __device__ __forceinline__ void ph_attn(const TI ti, CArgs& a, int l, bool ctx_out, unsigned char* ldsg) {
;     const int lane = ti.tid & 63;
;     const float gqm = fabsf(a.in[12][l * 64 + lane]), gkm = fabsf(a.in[13][l * 64 + lane]);
;     float mq = gqm, mk = gkm;
; #pragma unroll
;     for (int o = 1; o < 64; o <<= 1) { mq = fmaxf(mq, __shfl_xor(mq, o)); mk = fmaxf(mk, __shfl_xor(mk, o)); }
;     const float mfix = 8.f * mq * mk * 1.4426950408889634f * 1.03f;
;     const float* lp = a.in[14] + l * 256;
;     const float s1 = wave_sum(lp[lane] * lp[64 + lane]), s2 = wave_sum(lp[128 + lane] * lp[192 + lane]);
;     const float lam_init = 0.8f - 0.6f * expf(-0.3f * (float)l);
;     const float lam = expf(s1) - expf(s2) + lam_init;
.LBB0_329:
	s_load_dwordx4 s[4:7], s[74:75], 0x60
	s_load_dwordx2 s[10:11], s[74:75], 0x70
	v_lshl_or_b32 v4, s62, 6, v180
	v_ashrrev_i32_e32 v5, 31, v4
	v_lshlrev_b64 v[4:5], 2, v[4:5]
	s_waitcnt lgkmcnt(0)
	v_lshl_add_u64 v[6:7], s[4:5], 0, v[4:5]
	s_lshl_b32 s4, s62, 8
	v_lshl_add_u64 v[4:5], s[6:7], 0, v[4:5]
	s_ashr_i32 s5, s4, 31
	global_load_dword v3, v[6:7], off
	s_lshl_b64 s[4:5], s[4:5], 2
	global_load_dword v6, v[4:5], off
	s_add_u32 s4, s10, s4
	s_addc_u32 s5, s11, s5
	v_lshl_add_u64 v[4:5], v[180:181], 2, s[4:5]
	global_load_dword v7, v[4:5], off
	global_load_dword v8, v[4:5], off offset:256
	global_load_dword v9, v[4:5], off offset:512
	s_nop 0
	global_load_dword v4, v[4:5], off offset:768
	v_xor_b32_e32 v5, 1, v173
	v_cmp_lt_i32_e32 vcc, v2, v0
	v_xor_b32_e32 v10, 2, v173
	v_xor_b32_e32 v11, 4, v173
	v_cndmask_b32_e32 v2, v173, v2, vcc
	v_cmp_lt_i32_e32 vcc, v5, v0
	v_xor_b32_e32 v12, 8, v173
	v_xor_b32_e32 v13, 16, v173
	v_cndmask_b32_e32 v5, v173, v5, vcc
	v_cmp_lt_i32_e32 vcc, v10, v0
	v_lshlrev_b32_e32 v137, 2, v2
	v_lshlrev_b32_e32 v2, 2, v5
	v_cndmask_b32_e32 v10, v173, v10, vcc
	v_cmp_lt_i32_e32 vcc, v11, v0
	v_lshlrev_b32_e32 v5, 2, v10
	s_and_b64 s[16:17], s[76:77], exec
	v_cndmask_b32_e32 v11, v173, v11, vcc
	v_cmp_lt_i32_e32 vcc, v12, v0
	v_lshlrev_b32_e32 v10, 2, v11
	s_movk_i32 s1, 0x480
	v_cndmask_b32_e32 v12, v173, v12, vcc
	v_cmp_lt_i32_e32 vcc, v13, v0
	v_lshlrev_b32_e32 v11, 2, v12
	s_cselect_b32 s1, s1, 0x400
	v_cndmask_b32_e32 v0, v173, v13, vcc
	v_lshlrev_b32_e32 v0, 2, v0
	s_cmp_ge_i32 s2, s1
	s_waitcnt vmcnt(0)
	v_and_b32_e32 v12, 0x7fffffff, v3
	ds_bpermute_b32 v12, v2, v12
	v_and_b32_e32 v13, 0x7fffffff, v6
	ds_bpermute_b32 v2, v2, v13
	v_max_f32_e64 v3, |v3|, |v3|
	v_max_f32_e64 v6, |v6|, |v6|
	v_mul_f32_e32 v14, v9, v4
	v_mul_f32_e32 v13, v7, v8
	s_waitcnt lgkmcnt(0)
	v_max_f32_e32 v2, v2, v2
	v_mov_b32_dpp v14, v14 quad_perm:[1,0,3,2] row_mask:0xf bank_mask:0xf bound_ctrl:1
	v_fmac_f32_e32 v14, v9, v4
	v_max_f32_e32 v4, v12, v12
	v_max_f32_e32 v3, v3, v4
	v_max_f32_e32 v2, v6, v2
	ds_bpermute_b32 v4, v5, v3
	ds_bpermute_b32 v5, v5, v2
	v_mov_b32_dpp v13, v13 quad_perm:[1,0,3,2] row_mask:0xf bank_mask:0xf bound_ctrl:1
	v_fmac_f32_e32 v13, v7, v8
	v_add_f32_dpp v7, v14, v14 quad_perm:[2,3,0,1] row_mask:0xf bank_mask:0xf bound_ctrl:1
	s_waitcnt lgkmcnt(1)
	v_max_f32_e32 v4, v4, v4
	s_waitcnt lgkmcnt(0)
	v_max_f32_e32 v5, v5, v5
	v_max_f32_e32 v3, v3, v4
	v_max_f32_e32 v2, v2, v5
	ds_bpermute_b32 v4, v10, v3
	ds_bpermute_b32 v5, v10, v2
	v_add_f32_dpp v6, v13, v13 quad_perm:[2,3,0,1] row_mask:0xf bank_mask:0xf bound_ctrl:1
	v_add_f32_dpp v7, v7, v7 row_half_mirror row_mask:0xf bank_mask:0xf bound_ctrl:1
	s_waitcnt lgkmcnt(1)
	v_max_f32_e32 v4, v4, v4
	s_waitcnt lgkmcnt(0)
	v_max_f32_e32 v5, v5, v5
	v_max_f32_e32 v3, v3, v4
	v_max_f32_e32 v2, v2, v5
	ds_bpermute_b32 v4, v11, v3
	ds_bpermute_b32 v5, v11, v2
	v_add_f32_dpp v6, v6, v6 row_half_mirror row_mask:0xf bank_mask:0xf bound_ctrl:1
	v_add_f32_dpp v7, v7, v7 row_mirror row_mask:0xf bank_mask:0xf bound_ctrl:1
	s_waitcnt lgkmcnt(1)
	v_max_f32_e32 v4, v4, v4
	s_waitcnt lgkmcnt(0)
	v_max_f32_e32 v5, v5, v5
	v_max_f32_e32 v3, v3, v4
	v_max_f32_e32 v2, v2, v5
	ds_bpermute_b32 v4, v0, v3
	ds_bpermute_b32 v0, v0, v2
	v_add_f32_dpp v6, v6, v6 row_mirror row_mask:0xf bank_mask:0xf bound_ctrl:1
	v_readlane_b32 s3, v7, 0
	v_readlane_b32 s10, v6, 0
	s_waitcnt lgkmcnt(1)
	v_max_f32_e32 v4, v4, v4
	s_waitcnt lgkmcnt(0)
	v_max_f32_e32 v5, v0, v0
	v_max_f32_e32 v0, v3, v4
	v_max_f32_e32 v3, v2, v5
	ds_bpermute_b32 v2, v137, v0
	ds_bpermute_b32 v4, v137, v3
	v_readlane_b32 s11, v6, 16
	v_readlane_b32 s7, v6, 32
	v_readlane_b32 s14, v6, 48
	v_readlane_b32 s4, v7, 16
	v_readlane_b32 s5, v7, 32
	v_readlane_b32 s6, v7, 48
	s_cbranch_scc1 .LBB0_364
; #define LAS __attribute__((address_space(3)))
; __device__ __forceinline__ void attn_unit(const TI ti, CArgs& a, int b, int hd, int qrow0, int st_lo, int st_hi, float mfix, float lam, float lam_init, const float* subg, unsigned char* ldsg) {
;     const int tid = ti.tid, lane = tid & 63, w = tid >> 6, r = lane & 31, h = lane >> 5, qt = w >> 1, c = w & 1;
;     bf16_t* Qb = (bf16_t*)(a.ws + WS_Q); const bf16_t* Kb = (const bf16_t*)(a.ws + WS_K); const bf16_t* Vb = (const bf16_t*)(a.ws + WS_V);
;     LAS unsigned char* L = (LAS unsigned char*)ldsg;
;     constexpr int KOFF = 0, VOFF = 17408, BUFB = 35840;
;     bf16x8 qf[4];
;     { const bf16_t* qp = Qb + (size_t)(qrow0 + qt * 32 + r) * 1024 + hd * 128 + c * 64 + 8 * h;
; #pragma unroll
;       for (int ks = 0; ks < 4; ++ks) qf[ks] = *(const bf16x8*)(qp + 16 * ks); }
;     f32x16 O[4];
; #pragma unroll
;     for (int e = 0; e < 4; ++e)
; #pragma unroll
;         for (int i = 0; i < 16; ++i) O[e][i] = 0.f;
;     float lsum = 0.f;
;     u32x4 kreg[2], vreg[2];
;     typedef const __attribute__((address_space(1))) u32x4* gc16_t;
;     const int koff0 = (tid >> 4) * 1024 + (tid & 15) * 8, koff1 = koff0 + 32 * 1024, voff = lane * 1024 + w * 16;
; __device__ __forceinline__ void ph_attn(const TI ti, CArgs& a, int l, bool ctx_out, unsigned char* ldsg) {
;     ...
;     const float mfix = 8.f * mq * mk * 1.4426950408889634f * 1.03f;
;     const float* lp = a.in[14] + l * 256;
;     const float s1 = wave_sum(lp[lane] * lp[64 + lane]), s2 = wave_sum(lp[128 + lane] * lp[192 + lane]);
;     const float lam_init = 0.8f - 0.6f * expf(-0.3f * (float)l);
;     const float lam = expf(s1) - expf(s2) + lam_init;
;     const float* subg = a.in[15] + l * 128;
;     const int nun = 1024 + (ctx_out ? 128 : 0);
;     for (int u = ti.bid; u < nun; u += ti.nblk) {
;         if (u < 1024) { const int bh = u >> 4, qb = u & 15; attn_unit(ti, a, bh >> 3, bh & 7, (bh >> 3) * 2048 + qb * 128, 0, 36, mfix, lam, lam_init, subg, ldsg); }
;         else { const int v = u - 1024, bh = v >> 1, qb = v & 1; attn_unit(ti, a, bh >> 3, bh & 7, ML + (bh >> 3) * 256 + qb * 128, 32, 36, mfix, lam, lam_init, subg, ldsg); }
	v_cvt_f32_i32_e32 v5, s62
	s_mov_b32 s16, 0x3fb8aa3b
	s_waitcnt lgkmcnt(1)
	v_max_f32_e32 v2, v2, v2
	v_max_f32_e32 v0, v0, v0
	v_mul_f32_e32 v5, 0xbe99999a, v5
	v_mul_f32_e32 v6, 0x3fb8aa3b, v5
	v_fma_f32 v7, v5, s16, -v6
	v_rndne_f32_e32 v8, v6
	v_fmac_f32_e32 v7, 0x32a5705f, v5
	v_sub_f32_e32 v6, v6, v8
	v_add_f32_e32 v6, v6, v7
	v_cvt_i32_f32_e32 v8, v8
	v_exp_f32_e32 v6, v6
	v_mov_b32_e32 v7, s11
	v_add_f32_e32 v7, s10, v7
	s_mov_b32 s10, 0xc2ce8ed0
	v_ldexp_f32 v6, v6, v8
	v_mov_b32_e32 v8, s14
	v_add_f32_e32 v8, s7, v8
	v_add_f32_e32 v7, v7, v8
	v_mul_f32_e32 v8, 0x3fb8aa3b, v7
	v_fma_f32 v9, v7, s16, -v8
	v_rndne_f32_e32 v10, v8
	v_fmac_f32_e32 v9, 0x32a5705f, v7
	v_sub_f32_e32 v8, v8, v10
	v_add_f32_e32 v8, v8, v9
	v_exp_f32_e32 v8, v8
	v_cvt_i32_f32_e32 v9, v10
	v_cmp_ngt_f32_e32 vcc, s10, v5
	s_mov_b32 s7, 0x42b17218
	s_waitcnt lgkmcnt(0)
	v_max_f32_e32 v4, v4, v4
	v_cndmask_b32_e32 v6, 0, v6, vcc
	v_cmp_nlt_f32_e32 vcc, s7, v5
	v_max_f32_e32 v3, v3, v3
	v_max_f32_e32 v0, v0, v2
	v_cndmask_b32_e32 v5, v191, v6, vcc
	v_mov_b32_e32 v6, 0x3f4ccccd
	v_fmamk_f32 v18, v5, 0xbf19999a, v6
	v_ldexp_f32 v5, v8, v9
	v_mov_b32_e32 v6, s4
	v_mov_b32_e32 v8, s6
	v_add_f32_e32 v6, s3, v6
	v_add_f32_e32 v8, s5, v8
	v_add_f32_e32 v6, v6, v8
	v_mul_f32_e32 v8, 0x3fb8aa3b, v6
	v_fma_f32 v9, v6, s16, -v8
	v_rndne_f32_e32 v10, v8
	v_fmac_f32_e32 v9, 0x32a5705f, v6
	v_sub_f32_e32 v8, v8, v10
	v_add_f32_e32 v8, v8, v9
	v_exp_f32_e32 v8, v8
	v_cvt_i32_f32_e32 v9, v10
	v_cmp_ngt_f32_e32 vcc, s10, v7
	s_load_dwordx2 s[4:5], s[74:75], 0x78
	s_lshl_b32 s6, s62, 7
	v_cndmask_b32_e32 v5, 0, v5, vcc
	v_cmp_nlt_f32_e32 vcc, s7, v7
	v_ldexp_f32 v7, v8, v9
	v_max_f32_e32 v3, v3, v4
	v_cndmask_b32_e32 v5, v191, v5, vcc
	v_cmp_ngt_f32_e32 vcc, s10, v6
	s_load_dwordx2 s[10:11], s[74:75], 0x110
	v_mul_f32_e32 v0, 0x41000000, v0
	v_cndmask_b32_e32 v7, 0, v7, vcc
	v_cmp_nlt_f32_e32 vcc, s7, v6
	s_ashr_i32 s7, s6, 31
	s_lshl_b64 s[6:7], s[6:7], 2
	s_waitcnt lgkmcnt(0)
	s_add_u32 s4, s4, s6
	s_addc_u32 s5, s5, s7
	s_add_u32 s46, s10, 0xa600000
	s_addc_u32 s47, s11, 0
	s_add_u32 s3, s10, 0xca00000
	s_addc_u32 s6, s11, 0
	s_add_u32 s7, s10, 0xee00000
	v_lshlrev_b32_e32 v4, 3, v178
	v_mul_f32_e32 v0, v3, v0
	v_ashrrev_i32_e32 v3, 6, v178
	s_addc_u32 s10, s11, 0
	v_lshlrev_b32_e32 v2, 6, v178
	v_and_b32_e32 v4, 0x78, v4
	s_movk_i32 s11, 0xfc00
	v_and_or_b32 v140, v2, s11, v4
	v_lshlrev_b32_e32 v2, 4, v3
	v_lshl_add_u32 v142, v180, 10, v2
	v_lshlrev_b32_e32 v2, 4, v178
	v_and_b32_e32 v147, 0xf0, v2
	v_lshrrev_b32_e32 v2, 4, v178
	s_movk_i32 s14, 0x110
	v_mul_lo_u32 v155, v2, s14
	v_add_u32_e32 v2, 0x200, v178
	v_lshrrev_b32_e32 v2, 4, v2
	s_movk_i32 s11, 0x480
	v_cndmask_b32_e32 v6, v191, v7, vcc
	v_mul_lo_u32 v156, v2, s14
	v_mul_lo_u32 v2, v3, s11
	v_sub_f32_e32 v5, v5, v6
	v_lshlrev_b32_e32 v157, 1, v2
	v_lshlrev_b32_e32 v2, 1, v178
	v_lshrrev_b32_e32 v4, 1, v178
	v_add_f32_e32 v134, v18, v5
	v_lshrrev_b32_e32 v20, 5, v180
	v_and_b32_e32 v22, 1, v3
	v_and_b32_e32 v2, 8, v2
	v_and_b32_e32 v4, 4, v4
	v_and_b32_e32 v5, 51, v178
	v_mul_f32_e32 v0, 0x3fb8aa3b, v0
	v_lshlrev_b32_e32 v136, 6, v22
	v_lshlrev_b32_e32 v138, 3, v20
	v_or3_b32 v2, v2, v5, v4
	v_lshlrev_b32_e32 v158, 1, v2
	v_mul_f32_e32 v2, 0xbf83d70a, v0
	v_or_b32_e32 v0, v136, v138
	v_lshlrev_b32_e32 v144, 4, v20
	v_and_b32_e32 v19, 31, v178
	v_ashrrev_i32_e32 v21, 7, v178
	v_lshlrev_b32_e32 v161, 1, v0
	v_mov_b32_e32 v0, 0x3600
	s_movk_i32 s11, 0x90
	v_add_u32_e32 v166, 0, v144
	v_lshl_or_b32 v139, v21, 5, v19
	v_mad_u32_u24 v163, v19, s11, v0
	v_lshlrev_b32_e32 v0, 14, v21
	v_lshlrev_b32_e32 v21, 2, v180
	v_mov_b32_e32 v145, v1
	v_mad_u32_u24 v167, v19, s11, v166
	v_ashrrev_i32_e32 v141, 31, v140
	v_ashrrev_i32_e32 v143, 31, v142
	v_add_u32_e32 v154, 0, v147
	v_add3_u32 v159, 0, v157, v158
	v_cmp_lt_i32_e64 s[40:41], 3, v3
	v_mul_u32_u24_e32 v160, 0x110, v19
	v_mov_b32_e32 v3, v2
	v_mov_b32_e32 v4, v2
	v_mov_b32_e32 v5, v2
	v_mov_b32_e32 v6, v2
	v_mov_b32_e32 v7, v2
	v_mov_b32_e32 v8, v2
	v_mov_b32_e32 v9, v2
	v_mov_b32_e32 v10, v2
	v_mov_b32_e32 v11, v2
	v_mov_b32_e32 v12, v2
	v_mov_b32_e32 v13, v2
	v_mov_b32_e32 v14, v2
	v_mov_b32_e32 v15, v2
	v_mov_b32_e32 v16, v2
	v_mov_b32_e32 v17, v2
	v_mul_u32_u24_e32 v162, 0x90, v19
	v_cmp_eq_u32_e64 s[42:43], 0, v22
	v_cmp_eq_u32_e64 s[44:45], 1, v22
	v_add3_u32 v164, 0, v0, v21
	v_sub_f32_e32 v165, 1.0, v18
	v_lshlrev_b32_e32 v146, 2, v20
	v_lshl_add_u64 v[148:149], s[4:5], 0, v[144:145]
	v_mad_u32_u24 v145, v19, s14, 0
	v_add_u32_e32 v168, 0xc200, v167
	v_mov_b32_e32 v135, v134
	s_mov_b32 s16, s2
	s_cmp_lg_u32 s0, 0x100
	s_cbranch_scc1 .Lattn_noperm
	s_and_b32 s16, s2, 7
	s_lshl_b32 s16, s16, 5
	s_lshr_b32 s11, s2, 3
	s_or_b32 s16, s16, s11
.Lattn_noperm:
	s_lshl_b32 s11, s16, 4
	s_lshl_b32 s14, s0, 4
	s_branch .LBB0_333

; #define LAS __attribute__((address_space(3)))
; #define ATT_QK(SX, sub) do { __builtin_amdgcn_s_setprio(1); _Pragma("unroll") for (int ks = 0; ks < 4; ++ks) { \
;             const bf16x8 kf = *(LAS const bf16x8*)(Bb + KOFF + ((sub) * 32 + r) * 272 + (c * 64 + 16 * ks + 8 * h) * 2); SX = MFMA32(kf, qf[ks], SX); } __builtin_amdgcn_s_setprio(0); } while (0)
; #define ATT_SOFT(SX, P0, P1) do { float p[16]; _Pragma("unroll") for (int i = 0; i < 16; ++i) { p[i] = __builtin_amdgcn_exp2f(SX[i]); lsum += p[i]; } \
;             P0 = pk8f(p[0], p[1], p[2], p[3], p[4], p[5], p[6], p[7]); P1 = pk8f(p[8], p[9], p[10], p[11], p[12], p[13], p[14], p[15]); } while (0)
; #define ATT_PV(sub, P0, P1) do { __builtin_amdgcn_s_setprio(1); _Pragma("unroll") for (int et = 0; et < 4; ++et) { _Pragma("unroll") for (int s = 0; s < 2; ++s) { \
;             const bf16x8 vf = *(LAS const bf16x8*)(Bb + VOFF + (et * 32 + r) * 144 + ((sub) * 32 + 16 * s + 8 * h) * 2); O[et] = MFMA32(vf, s ? P1 : P0, O[et]); } } __builtin_amdgcn_s_setprio(0); } while (0)
; __device__ __forceinline__ void attn_unit(const TI ti, CArgs& a, int b, int hd, int qrow0, int st_lo, int st_hi, float mfix, float lam, float lam_init, const float* subg, unsigned char* ldsg) {
;     ...
;     for (int st = st_lo; st < st_hi; ++st) {
;         const int bi = (st - st_lo) & 1;
;         if (st + 1 < st_hi) ATT_LOAD(st + 1);
;         LAS const unsigned char* Bb = L + bi * BUFB;
;         f32x16 Sx0, Sx1; bf16x8 pa0, pa1, pc0, pc1;
; #pragma unroll
;         for (int i = 0; i < 16; ++i) { Sx0[i] = -mfix; Sx1[i] = -mfix; }
;     ...
;         if (w < 4) {
;             ATT_QK(Sx0, 0); ATT_QK(Sx1, 1);
;             __builtin_amdgcn_sched_barrier(0);
;             ATT_SOFT(Sx0, pa0, pa1); ATT_PV(0, pa0, pa1);
;             ATT_SOFT(Sx1, pc0, pc1); ATT_PV(1, pc0, pc1);
;         } else {
;             ATT_QK(Sx0, 0);
;             __builtin_amdgcn_sched_barrier(0);
;             ATT_SOFT(Sx0, pa0, pa1);
;             __builtin_amdgcn_sched_barrier(0);
;             ATT_QK(Sx1, 1); ATT_PV(0, pa0, pa1);
;             __builtin_amdgcn_sched_barrier(0);
;             ATT_SOFT(Sx1, pc0, pc1); ATT_PV(1, pc0, pc1);
;         }
.LBB0_352:
	s_and_b32 s48, s17, 1
	s_cmp_lt_u32 s17, 31
	s_cselect_b32 s4, s39, s37
	s_ashr_i32 s5, s4, 31
	s_lshl_b64 s[4:5], s[4:5], 11
	s_add_u32 s33, s27, s4
	s_addc_u32 s36, s34, s5
	v_mov_b32_e32 v82, s33
	v_mov_b32_e32 v83, s36
	s_add_u32 s4, s18, s4
	s_addc_u32 s5, s35, s5
	v_lshl_add_u64 v[82:83], v[140:141], 1, v[82:83]
	v_mov_b32_e32 v84, s4
	v_mov_b32_e32 v85, s5
	v_add_co_u32_e32 v86, vcc, s79, v82
	s_mul_i32 s4, s48, 0x8c00
	s_nop 0
	v_addc_co_u32_e32 v87, vcc, 0, v83, vcc
	global_load_dwordx4 v[122:125], v[82:83], off
	global_load_dwordx4 v[126:129], v[86:87], off
	v_lshl_add_u64 v[82:83], v[142:143], 1, v[84:85]
	global_load_dwordx4 v[118:121], v[82:83], off
	global_load_dwordx4 v[114:117], v[82:83], off offset:16
	s_add_i32 s4, s4, 0
	s_setprio 1
	v_add_u32_e32 v82, s4, v160
	v_add_u32_e32 v151, v82, v161
	ds_read_b128 v[130:133], v151
	v_add3_u32 v150, s4, v144, v162
	s_and_saveexec_b64 s[4:5], s[40:41]
	s_xor_b64 s[4:5], exec, s[4:5]
	s_cbranch_execz .LBB0_354
	ds_read_b128 v[182:185], v151 offset:32
	ds_read_b128 v[198:201], v151 offset:64
	ds_read_b128 v[202:205], v151 offset:96
	ds_read_b128 v[206:209], v151 offset:8704
	ds_read_b128 v[210:213], v151 offset:8736
	ds_read_b128 v[236:239], v151 offset:8768
	ds_read_b128 v[240:243], v151 offset:8800
	s_setprio 1
	s_waitcnt lgkmcnt(7)
	v_mfma_f32_32x32x16_bf16 v[82:97], v[130:133], v[110:113], v[2:17]
	s_waitcnt lgkmcnt(6)
	v_mfma_f32_32x32x16_bf16 v[82:97], v[182:185], v[106:109], v[82:97]
	s_waitcnt lgkmcnt(5)
	v_mfma_f32_32x32x16_bf16 v[82:97], v[198:201], v[102:105], v[82:97]
	s_waitcnt lgkmcnt(4)
	v_mfma_f32_32x32x16_bf16 v[82:97], v[202:205], v[98:101], v[82:97]
	ds_read_b128 v[130:133], v150 offset:17408
	ds_read_b128 v[182:185], v150 offset:17440
	ds_read_b128 v[198:201], v150 offset:22016
	ds_read_b128 v[202:205], v150 offset:22048
	s_waitcnt lgkmcnt(7)
	v_mfma_f32_32x32x16_bf16 v[220:235], v[206:209], v[110:113], v[2:17]
	s_waitcnt lgkmcnt(6)
	v_mfma_f32_32x32x16_bf16 v[220:235], v[210:213], v[106:109], v[220:235]
	s_waitcnt lgkmcnt(5)
	v_mfma_f32_32x32x16_bf16 v[220:235], v[236:239], v[102:105], v[220:235]
	s_waitcnt lgkmcnt(4)
	v_mfma_f32_32x32x16_bf16 v[220:235], v[240:243], v[98:101], v[220:235]
	ds_read_b128 v[206:209], v150 offset:26624
	ds_read_b128 v[210:213], v150 offset:26656
	ds_read_b128 v[236:239], v150 offset:31232
	ds_read_b128 v[240:243], v150 offset:31264
	s_setprio 0
	v_exp_f32_e32 v169, v82
	v_exp_f32_e32 v170, v83
	v_exp_f32_e32 v171, v84
	v_exp_f32_e32 v174, v85
	v_exp_f32_e32 v175, v86
	v_exp_f32_e32 v176, v87
	v_exp_f32_e32 v177, v88
	v_exp_f32_e32 v179, v89
	v_exp_f32_e32 v90, v90
	v_exp_f32_e32 v91, v91
	v_exp_f32_e32 v92, v92
	v_exp_f32_e32 v93, v93
	v_exp_f32_e32 v94, v94
	v_exp_f32_e32 v95, v95
	v_exp_f32_e32 v96, v96
	v_exp_f32_e32 v97, v97
	v_cvt_pk_bf16_f32 v82, v169, v170
	v_cvt_pk_bf16_f32 v83, v171, v174
	v_cvt_pk_bf16_f32 v84, v175, v176
	v_cvt_pk_bf16_f32 v85, v177, v179
	v_cvt_pk_bf16_f32 v86, v90, v91
	v_cvt_pk_bf16_f32 v87, v92, v93
	v_cvt_pk_bf16_f32 v88, v94, v95
	v_cvt_pk_bf16_f32 v89, v96, v97
	s_setprio 1
	s_waitcnt lgkmcnt(7)
	v_mfma_f32_32x32x16_bf16 v[18:33], v[130:133], v[82:85], v[18:33]
	v_add_f32_e32 v0, v169, v0
	v_add_f32_e32 v0, v170, v0
	s_waitcnt lgkmcnt(6)
	v_mfma_f32_32x32x16_bf16 v[18:33], v[182:185], v[86:89], v[18:33]
	v_add_f32_e32 v0, v171, v0
	v_add_f32_e32 v0, v174, v0
	ds_read_b128 v[130:133], v150 offset:17472
	ds_read_b128 v[182:185], v150 offset:17504
	s_waitcnt lgkmcnt(7)
	v_mfma_f32_32x32x16_bf16 v[34:49], v[198:201], v[82:85], v[34:49]
	v_add_f32_e32 v0, v175, v0
	v_add_f32_e32 v0, v176, v0
	s_waitcnt lgkmcnt(6)
	v_mfma_f32_32x32x16_bf16 v[34:49], v[202:205], v[86:89], v[34:49]
	v_add_f32_e32 v0, v177, v0
	v_add_f32_e32 v0, v179, v0
	ds_read_b128 v[198:201], v150 offset:22080
	ds_read_b128 v[202:205], v150 offset:22112
	s_waitcnt lgkmcnt(7)
	v_mfma_f32_32x32x16_bf16 v[66:81], v[206:209], v[82:85], v[66:81]
	v_add_f32_e32 v0, v90, v0
	v_add_f32_e32 v0, v91, v0
	s_waitcnt lgkmcnt(6)
	v_mfma_f32_32x32x16_bf16 v[66:81], v[210:213], v[86:89], v[66:81]
	v_add_f32_e32 v0, v92, v0
	v_add_f32_e32 v0, v93, v0
	ds_read_b128 v[206:209], v150 offset:26688
	ds_read_b128 v[210:213], v150 offset:26720
	s_waitcnt lgkmcnt(7)
	v_mfma_f32_32x32x16_bf16 v[50:65], v[236:239], v[82:85], v[50:65]
	v_add_f32_e32 v0, v94, v0
	v_add_f32_e32 v0, v95, v0
	s_waitcnt lgkmcnt(6)
	v_mfma_f32_32x32x16_bf16 v[50:65], v[240:243], v[86:89], v[50:65]
	v_add_f32_e32 v0, v96, v0
	v_add_f32_e32 v0, v97, v0
	ds_read_b128 v[236:239], v150 offset:31296
	ds_read_b128 v[240:243], v150 offset:31328
	s_setprio 0
	v_exp_f32_e32 v181, v220
	v_exp_f32_e32 v197, v221
	v_exp_f32_e32 v214, v222
	v_exp_f32_e32 v244, v223
	v_exp_f32_e32 v245, v224
	v_exp_f32_e32 v246, v225
	v_exp_f32_e32 v247, v226
	v_exp_f32_e32 v248, v227
	v_exp_f32_e32 v228, v228
	v_exp_f32_e32 v229, v229
	v_exp_f32_e32 v230, v230
	v_exp_f32_e32 v231, v231
	v_exp_f32_e32 v232, v232
	v_exp_f32_e32 v233, v233
	v_exp_f32_e32 v234, v234
	v_exp_f32_e32 v235, v235
	v_cvt_pk_bf16_f32 v220, v181, v197
	v_cvt_pk_bf16_f32 v221, v214, v244
	v_cvt_pk_bf16_f32 v222, v245, v246
	v_cvt_pk_bf16_f32 v223, v247, v248
	v_cvt_pk_bf16_f32 v224, v228, v229
	v_cvt_pk_bf16_f32 v225, v230, v231
	v_cvt_pk_bf16_f32 v226, v232, v233
	v_cvt_pk_bf16_f32 v227, v234, v235
	s_setprio 1
	s_waitcnt lgkmcnt(7)
	v_mfma_f32_32x32x16_bf16 v[18:33], v[130:133], v[220:223], v[18:33]
	v_add_f32_e32 v0, v181, v0
	v_add_f32_e32 v0, v197, v0
	s_waitcnt lgkmcnt(6)
	v_mfma_f32_32x32x16_bf16 v[18:33], v[182:185], v[224:227], v[18:33]
	v_add_f32_e32 v0, v214, v0
	v_add_f32_e32 v0, v244, v0
	s_waitcnt lgkmcnt(5)
	v_mfma_f32_32x32x16_bf16 v[34:49], v[198:201], v[220:223], v[34:49]
	v_add_f32_e32 v0, v245, v0
	v_add_f32_e32 v0, v246, v0
	s_waitcnt lgkmcnt(4)
	v_mfma_f32_32x32x16_bf16 v[34:49], v[202:205], v[224:227], v[34:49]
	v_add_f32_e32 v0, v247, v0
	v_add_f32_e32 v0, v248, v0
	s_waitcnt lgkmcnt(3)
	v_mfma_f32_32x32x16_bf16 v[66:81], v[206:209], v[220:223], v[66:81]
	v_add_f32_e32 v0, v228, v0
	v_add_f32_e32 v0, v229, v0
	s_waitcnt lgkmcnt(2)
	v_mfma_f32_32x32x16_bf16 v[66:81], v[210:213], v[224:227], v[66:81]
	v_add_f32_e32 v0, v230, v0
	v_add_f32_e32 v0, v231, v0
	s_waitcnt lgkmcnt(1)
	v_mfma_f32_32x32x16_bf16 v[50:65], v[236:239], v[220:223], v[50:65]
	v_add_f32_e32 v0, v232, v0
	v_add_f32_e32 v0, v233, v0
	s_waitcnt lgkmcnt(0)
	v_mfma_f32_32x32x16_bf16 v[50:65], v[240:243], v[224:227], v[50:65]
	v_add_f32_e32 v0, v234, v0
	v_add_f32_e32 v0, v235, v0
; #define LAS __attribute__((address_space(3)))
; #define ATT_QK(SX, sub) do { __builtin_amdgcn_s_setprio(1); _Pragma("unroll") for (int ks = 0; ks < 4; ++ks) { \
;             const bf16x8 kf = *(LAS const bf16x8*)(Bb + KOFF + ((sub) * 32 + r) * 272 + (c * 64 + 16 * ks + 8 * h) * 2); SX = MFMA32(kf, qf[ks], SX); } __builtin_amdgcn_s_setprio(0); } while (0)
; #define ATT_SOFT(SX, P0, P1) do { float p[16]; _Pragma("unroll") for (int i = 0; i < 16; ++i) { p[i] = __builtin_amdgcn_exp2f(SX[i]); lsum += p[i]; } \
;             P0 = pk8f(p[0], p[1], p[2], p[3], p[4], p[5], p[6], p[7]); P1 = pk8f(p[8], p[9], p[10], p[11], p[12], p[13], p[14], p[15]); } while (0)
; #define ATT_PV(sub, P0, P1) do { __builtin_amdgcn_s_setprio(1); _Pragma("unroll") for (int et = 0; et < 4; ++et) { _Pragma("unroll") for (int s = 0; s < 2; ++s) { \
;             const bf16x8 vf = *(LAS const bf16x8*)(Bb + VOFF + (et * 32 + r) * 144 + ((sub) * 32 + 16 * s + 8 * h) * 2); O[et] = MFMA32(vf, s ? P1 : P0, O[et]); } } __builtin_amdgcn_s_setprio(0); } while (0)
; __device__ __forceinline__ void attn_unit(const TI ti, CArgs& a, int b, int hd, int qrow0, int st_lo, int st_hi, float mfix, float lam, float lam_init, const float* subg, unsigned char* ldsg) {
;     ...
;     for (int st = st_lo; st < st_hi; ++st) {
;         const int bi = (st - st_lo) & 1;
;         if (st + 1 < st_hi) ATT_LOAD(st + 1);
;         LAS const unsigned char* Bb = L + bi * BUFB;
;         f32x16 Sx0, Sx1; bf16x8 pa0, pa1, pc0, pc1;
; #pragma unroll
;         for (int i = 0; i < 16; ++i) { Sx0[i] = -mfix; Sx1[i] = -mfix; }
;     ...
;         if (w < 4) {
;             ATT_QK(Sx0, 0); ATT_QK(Sx1, 1);
;             __builtin_amdgcn_sched_barrier(0);
;             ATT_SOFT(Sx0, pa0, pa1); ATT_PV(0, pa0, pa1);
;             ATT_SOFT(Sx1, pc0, pc1); ATT_PV(1, pc0, pc1);
;         } else {
;             ATT_QK(Sx0, 0);
;             __builtin_amdgcn_sched_barrier(0);
;             ATT_SOFT(Sx0, pa0, pa1);
;             __builtin_amdgcn_sched_barrier(0);
;             ATT_QK(Sx1, 1); ATT_PV(0, pa0, pa1);
;             __builtin_amdgcn_sched_barrier(0);
;             ATT_SOFT(Sx1, pc0, pc1); ATT_PV(1, pc0, pc1);
;         }
.LBB0_354:
	s_andn2_saveexec_b64 s[4:5], s[4:5]
	s_cbranch_execz .LBB0_351
	ds_read_b128 v[182:185], v151 offset:32
	ds_read_b128 v[198:201], v151 offset:64
	ds_read_b128 v[202:205], v151 offset:96
	ds_read_b128 v[206:209], v151 offset:8704
	ds_read_b128 v[210:213], v151 offset:8736
	ds_read_b128 v[236:239], v151 offset:8768
	ds_read_b128 v[240:243], v151 offset:8800
	s_setprio 1
	s_waitcnt lgkmcnt(7)
	v_mfma_f32_32x32x16_bf16 v[82:97], v[130:133], v[110:113], v[2:17]
	s_waitcnt lgkmcnt(6)
	v_mfma_f32_32x32x16_bf16 v[82:97], v[182:185], v[106:109], v[82:97]
	s_waitcnt lgkmcnt(5)
	v_mfma_f32_32x32x16_bf16 v[82:97], v[198:201], v[102:105], v[82:97]
	s_waitcnt lgkmcnt(4)
	v_mfma_f32_32x32x16_bf16 v[82:97], v[202:205], v[98:101], v[82:97]
	ds_read_b128 v[130:133], v150 offset:17408
	ds_read_b128 v[182:185], v150 offset:17440
	ds_read_b128 v[198:201], v150 offset:22016
	ds_read_b128 v[202:205], v150 offset:22048
	s_setprio 0
	s_nop 6
	v_exp_f32_e32 v169, v82
	v_exp_f32_e32 v170, v83
	v_exp_f32_e32 v171, v84
	v_exp_f32_e32 v174, v85
	v_exp_f32_e32 v175, v86
	v_exp_f32_e32 v176, v87
	v_exp_f32_e32 v177, v88
	v_exp_f32_e32 v179, v89
	v_exp_f32_e32 v90, v90
	v_exp_f32_e32 v91, v91
	v_exp_f32_e32 v92, v92
	v_exp_f32_e32 v93, v93
	v_exp_f32_e32 v94, v94
	v_exp_f32_e32 v95, v95
	v_exp_f32_e32 v96, v96
	v_exp_f32_e32 v97, v97
	v_cvt_pk_bf16_f32 v82, v169, v170
	v_cvt_pk_bf16_f32 v83, v171, v174
	v_cvt_pk_bf16_f32 v84, v175, v176
	v_cvt_pk_bf16_f32 v85, v177, v179
	v_cvt_pk_bf16_f32 v86, v90, v91
	v_cvt_pk_bf16_f32 v87, v92, v93
	v_cvt_pk_bf16_f32 v88, v94, v95
	v_cvt_pk_bf16_f32 v89, v96, v97
	s_setprio 1
	s_waitcnt lgkmcnt(7)
	v_mfma_f32_32x32x16_bf16 v[220:235], v[206:209], v[110:113], v[2:17]
	s_waitcnt lgkmcnt(6)
	v_mfma_f32_32x32x16_bf16 v[220:235], v[210:213], v[106:109], v[220:235]
	s_waitcnt lgkmcnt(5)
	v_mfma_f32_32x32x16_bf16 v[220:235], v[236:239], v[102:105], v[220:235]
	s_waitcnt lgkmcnt(4)
	v_mfma_f32_32x32x16_bf16 v[220:235], v[240:243], v[98:101], v[220:235]
	ds_read_b128 v[206:209], v150 offset:26624
	ds_read_b128 v[210:213], v150 offset:26656
	ds_read_b128 v[236:239], v150 offset:31232
	ds_read_b128 v[240:243], v150 offset:31264
	s_waitcnt lgkmcnt(7)
	v_mfma_f32_32x32x16_bf16 v[18:33], v[130:133], v[82:85], v[18:33]
	v_add_f32_e32 v0, v169, v0
	v_add_f32_e32 v0, v170, v0
	s_waitcnt lgkmcnt(6)
	v_mfma_f32_32x32x16_bf16 v[18:33], v[182:185], v[86:89], v[18:33]
	v_add_f32_e32 v0, v171, v0
	v_add_f32_e32 v0, v174, v0
	ds_read_b128 v[130:133], v150 offset:17472
	ds_read_b128 v[182:185], v150 offset:17504
	s_waitcnt lgkmcnt(7)
	v_mfma_f32_32x32x16_bf16 v[34:49], v[198:201], v[82:85], v[34:49]
	v_add_f32_e32 v0, v175, v0
	v_add_f32_e32 v0, v176, v0
	s_waitcnt lgkmcnt(6)
	v_mfma_f32_32x32x16_bf16 v[34:49], v[202:205], v[86:89], v[34:49]
	v_add_f32_e32 v0, v177, v0
	v_add_f32_e32 v0, v179, v0
	ds_read_b128 v[198:201], v150 offset:22080
	ds_read_b128 v[202:205], v150 offset:22112
	s_waitcnt lgkmcnt(7)
	v_mfma_f32_32x32x16_bf16 v[66:81], v[206:209], v[82:85], v[66:81]
	v_add_f32_e32 v0, v90, v0
	v_add_f32_e32 v0, v91, v0
	s_waitcnt lgkmcnt(6)
	v_mfma_f32_32x32x16_bf16 v[66:81], v[210:213], v[86:89], v[66:81]
	v_add_f32_e32 v0, v92, v0
	v_add_f32_e32 v0, v93, v0
	ds_read_b128 v[206:209], v150 offset:26688
	ds_read_b128 v[210:213], v150 offset:26720
	s_waitcnt lgkmcnt(7)
	v_mfma_f32_32x32x16_bf16 v[50:65], v[236:239], v[82:85], v[50:65]
	v_add_f32_e32 v0, v94, v0
	v_add_f32_e32 v0, v95, v0
	s_waitcnt lgkmcnt(6)
	v_mfma_f32_32x32x16_bf16 v[50:65], v[240:243], v[86:89], v[50:65]
	v_add_f32_e32 v0, v96, v0
	v_add_f32_e32 v0, v97, v0
	ds_read_b128 v[236:239], v150 offset:31296
	ds_read_b128 v[240:243], v150 offset:31328
	s_setprio 0
	v_exp_f32_e32 v181, v220
	v_exp_f32_e32 v197, v221
	v_exp_f32_e32 v214, v222
	v_exp_f32_e32 v244, v223
	v_exp_f32_e32 v245, v224
	v_exp_f32_e32 v246, v225
	v_exp_f32_e32 v247, v226
	v_exp_f32_e32 v248, v227
	v_exp_f32_e32 v228, v228
	v_exp_f32_e32 v229, v229
	v_exp_f32_e32 v230, v230
	v_exp_f32_e32 v231, v231
	v_exp_f32_e32 v232, v232
	v_exp_f32_e32 v233, v233
	v_exp_f32_e32 v234, v234
	v_exp_f32_e32 v235, v235
	v_cvt_pk_bf16_f32 v220, v181, v197
	v_cvt_pk_bf16_f32 v221, v214, v244
	v_cvt_pk_bf16_f32 v222, v245, v246
	v_cvt_pk_bf16_f32 v223, v247, v248
	v_cvt_pk_bf16_f32 v224, v228, v229
	v_cvt_pk_bf16_f32 v225, v230, v231
	v_cvt_pk_bf16_f32 v226, v232, v233
	v_cvt_pk_bf16_f32 v227, v234, v235
	s_setprio 1
	s_waitcnt lgkmcnt(7)
	v_mfma_f32_32x32x16_bf16 v[18:33], v[130:133], v[220:223], v[18:33]
	v_add_f32_e32 v0, v181, v0
	v_add_f32_e32 v0, v197, v0
	s_waitcnt lgkmcnt(6)
	v_mfma_f32_32x32x16_bf16 v[18:33], v[182:185], v[224:227], v[18:33]
	v_add_f32_e32 v0, v214, v0
	v_add_f32_e32 v0, v244, v0
	s_waitcnt lgkmcnt(5)
	v_mfma_f32_32x32x16_bf16 v[34:49], v[198:201], v[220:223], v[34:49]
	v_add_f32_e32 v0, v245, v0
	v_add_f32_e32 v0, v246, v0
	s_waitcnt lgkmcnt(4)
	v_mfma_f32_32x32x16_bf16 v[34:49], v[202:205], v[224:227], v[34:49]
	v_add_f32_e32 v0, v247, v0
	v_add_f32_e32 v0, v248, v0
	s_waitcnt lgkmcnt(3)
	v_mfma_f32_32x32x16_bf16 v[66:81], v[206:209], v[220:223], v[66:81]
	v_add_f32_e32 v0, v228, v0
	v_add_f32_e32 v0, v229, v0
	s_waitcnt lgkmcnt(2)
	v_mfma_f32_32x32x16_bf16 v[66:81], v[210:213], v[224:227], v[66:81]
	v_add_f32_e32 v0, v230, v0
	v_add_f32_e32 v0, v231, v0
	s_waitcnt lgkmcnt(1)
	v_mfma_f32_32x32x16_bf16 v[50:65], v[236:239], v[220:223], v[50:65]
	v_add_f32_e32 v0, v232, v0
	v_add_f32_e32 v0, v233, v0
	s_waitcnt lgkmcnt(0)
	v_mfma_f32_32x32x16_bf16 v[50:65], v[240:243], v[224:227], v[50:65]
	v_add_f32_e32 v0, v234, v0
	v_add_f32_e32 v0, v235, v0
	s_branch .LBB0_351

; __device__ __forceinline__ void gmlp_unit(const TI ti, CArgs& a, int l, int u, unsigned char* ldsg) {
;     ...
;     for (int i = 0; i < 16; ++i) {
;         const int tok = w * 16 + i; const bf16_t* p = GV + (R0 + tok) * 1024 + lane * 16;
;         f32x4 x0, x1, x2, x3; unpack8(*(const u32x4*)p, x0, x1); unpack8(*(const u32x4*)(p + 8), x2, x3);
;         float ss = (x0.x * x0.x + x0.y * x0.y + x0.z * x0.z + x0.w * x0.w) + (x1.x * x1.x + x1.y * x1.y + x1.z * x1.z + x1.w * x1.w)
;                  + (x2.x * x2.x + x2.y * x2.y + x2.z * x2.z + x2.w * x2.w) + (x3.x * x3.x + x3.y * x3.y + x3.z * x3.z + x3.w * x3.w);
;         ss = wave_sum(ss);
;         if (lane == 0) rstd[tok] = rsqrtf(ss * (1.f / 1024.f) + 1e-6f);
;     }
.LBB0_438:
	v_lshl_add_u64 v[2:3], v[104:105], 0, s[46:47]
	v_add_co_u32_e32 v4, vcc, 0x8200000, v2
	s_nop 1
	v_addc_co_u32_e32 v5, vcc, 0, v3, vcc
	global_load_dwordx4 v[20:23], v[4:5], off
	global_load_dwordx4 v[24:27], v[4:5], off offset:16
	global_load_dwordx4 v[28:31], v[4:5], off offset:2048
	global_load_dwordx4 v[32:35], v[4:5], off offset:2064
	v_add_co_u32_e32 v4, vcc, 0x8201000, v2
	s_nop 1
	v_addc_co_u32_e32 v5, vcc, 0, v3, vcc
	global_load_dwordx4 v[36:39], v[4:5], off
	global_load_dwordx4 v[40:43], v[4:5], off offset:16
	global_load_dwordx4 v[44:47], v[4:5], off offset:2048
	global_load_dwordx4 v[48:51], v[4:5], off offset:2064
	s_waitcnt vmcnt(6)
	v_mov_b32_e32 v4, v20
	v_mov_b32_e32 v5, v21
	v_mov_b32_e32 v6, v22
	v_mov_b32_e32 v7, v23
	v_mov_b32_e32 v8, v24
	v_mov_b32_e32 v9, v25
	v_mov_b32_e32 v10, v26
	v_mov_b32_e32 v11, v27
	v_lshlrev_b32_e32 v12, 16, v4
	v_and_b32_e32 v4, 0xffff0000, v4
	v_lshlrev_b32_e32 v14, 16, v6
	v_and_b32_e32 v6, 0xffff0000, v6
	v_lshlrev_b32_e32 v16, 16, v8
	v_and_b32_e32 v8, 0xffff0000, v8
	v_mul_f32_e32 v4, v4, v4
	v_mul_f32_e32 v6, v6, v6
	v_lshlrev_b32_e32 v13, 16, v5
	v_lshlrev_b32_e32 v15, 16, v7
	v_lshlrev_b32_e32 v18, 16, v10
	v_and_b32_e32 v10, 0xffff0000, v10
	v_mul_f32_e32 v8, v8, v8
	v_fmac_f32_e32 v4, v12, v12
	v_fmac_f32_e32 v6, v14, v14
	v_and_b32_e32 v5, 0xffff0000, v5
	v_and_b32_e32 v7, 0xffff0000, v7
	v_lshlrev_b32_e32 v17, 16, v9
	v_mul_f32_e32 v10, v10, v10
	v_fmac_f32_e32 v8, v16, v16
	v_fmac_f32_e32 v4, v13, v13
	v_fmac_f32_e32 v6, v15, v15
	v_and_b32_e32 v9, 0xffff0000, v9
	v_lshlrev_b32_e32 v19, 16, v11
	v_fmac_f32_e32 v10, v18, v18
	v_fmac_f32_e32 v8, v17, v17
	v_fmac_f32_e32 v4, v5, v5
	v_fmac_f32_e32 v6, v7, v7
	v_and_b32_e32 v11, 0xffff0000, v11
	v_fmac_f32_e32 v10, v19, v19
	v_fmac_f32_e32 v8, v9, v9
	v_add_f32_e32 v4, v4, v6
	v_fmac_f32_e32 v10, v11, v11
	v_add_f32_e32 v4, v4, v8
	v_add_f32_e32 v4, v10, v4
	s_nop 1
	v_add_f32_dpp v4, v4, v4 quad_perm:[1,0,3,2] row_mask:0xf bank_mask:0xf bound_ctrl:1
	s_nop 1
	v_add_f32_dpp v4, v4, v4 quad_perm:[2,3,0,1] row_mask:0xf bank_mask:0xf bound_ctrl:1
	s_nop 1
	v_add_f32_dpp v4, v4, v4 row_half_mirror row_mask:0xf bank_mask:0xf bound_ctrl:1
	s_nop 1
	v_add_f32_dpp v4, v4, v4 row_mirror row_mask:0xf bank_mask:0xf bound_ctrl:1
	s_nop 0
	v_readlane_b32 s6, v4, 0
	v_readlane_b32 s3, v4, 16
	v_readlane_b32 s7, v4, 32
	v_readlane_b32 s11, v4, 48
	s_and_saveexec_b64 s[4:5], s[40:41]
	s_cbranch_execz .LBB0_440
	v_mov_b32_e32 v4, s3
	v_mov_b32_e32 v5, s11
	v_pk_add_f32 v[4:5], s[6:7], v[4:5]
	s_nop 0
	v_add_f32_e32 v4, v4, v5
	v_fmamk_f32 v4, v4, 0x3a800000, v172
	v_mul_f32_e32 v5, 0x4b800000, v4
	v_cmp_gt_f32_e32 vcc, s8, v4
	s_nop 1
	v_cndmask_b32_e32 v4, v4, v5, vcc
	v_rsq_f32_e32 v4, v4
	s_nop 0
	v_mul_f32_e32 v5, 0x45800000, v4
	v_cndmask_b32_e32 v4, v4, v5, vcc
	ds_write_b32 v0, v4
.LBB0_440:
	s_or_b64 exec, exec, s[4:5]
	s_waitcnt vmcnt(4)
	v_mov_b32_e32 v4, v28
	v_mov_b32_e32 v5, v29
	v_mov_b32_e32 v6, v30
	v_mov_b32_e32 v7, v31
	v_mov_b32_e32 v8, v32
	v_mov_b32_e32 v9, v33
	v_mov_b32_e32 v10, v34
	v_mov_b32_e32 v11, v35
	v_lshlrev_b32_e32 v12, 16, v4
	v_and_b32_e32 v4, 0xffff0000, v4
	v_lshlrev_b32_e32 v14, 16, v6
	v_and_b32_e32 v6, 0xffff0000, v6
	v_lshlrev_b32_e32 v16, 16, v8
	v_and_b32_e32 v8, 0xffff0000, v8
	v_mul_f32_e32 v4, v4, v4
	v_mul_f32_e32 v6, v6, v6
	v_lshlrev_b32_e32 v13, 16, v5
	v_lshlrev_b32_e32 v15, 16, v7
	v_lshlrev_b32_e32 v18, 16, v10
	v_and_b32_e32 v10, 0xffff0000, v10
	v_mul_f32_e32 v8, v8, v8
	v_fmac_f32_e32 v4, v12, v12
	v_fmac_f32_e32 v6, v14, v14
	v_and_b32_e32 v5, 0xffff0000, v5
	v_and_b32_e32 v7, 0xffff0000, v7
	v_lshlrev_b32_e32 v17, 16, v9
	v_mul_f32_e32 v10, v10, v10
	v_fmac_f32_e32 v8, v16, v16
	v_fmac_f32_e32 v4, v13, v13
	v_fmac_f32_e32 v6, v15, v15
	v_and_b32_e32 v9, 0xffff0000, v9
	v_lshlrev_b32_e32 v19, 16, v11
	v_fmac_f32_e32 v10, v18, v18
	v_fmac_f32_e32 v8, v17, v17
	v_fmac_f32_e32 v4, v5, v5
	v_fmac_f32_e32 v6, v7, v7
	v_and_b32_e32 v11, 0xffff0000, v11
	v_fmac_f32_e32 v10, v19, v19
	v_fmac_f32_e32 v8, v9, v9
	v_add_f32_e32 v4, v4, v6
	v_fmac_f32_e32 v10, v11, v11
	v_add_f32_e32 v4, v4, v8
	v_add_f32_e32 v4, v10, v4
	s_nop 1
	v_add_f32_dpp v4, v4, v4 quad_perm:[1,0,3,2] row_mask:0xf bank_mask:0xf bound_ctrl:1
	s_nop 1
	v_add_f32_dpp v4, v4, v4 quad_perm:[2,3,0,1] row_mask:0xf bank_mask:0xf bound_ctrl:1
	s_nop 1
	v_add_f32_dpp v4, v4, v4 row_half_mirror row_mask:0xf bank_mask:0xf bound_ctrl:1
	s_nop 1
	v_add_f32_dpp v4, v4, v4 row_mirror row_mask:0xf bank_mask:0xf bound_ctrl:1
	s_nop 0
	v_readlane_b32 s6, v4, 0
	v_readlane_b32 s3, v4, 16
	v_readlane_b32 s7, v4, 32
	v_readlane_b32 s11, v4, 48
	s_and_saveexec_b64 s[4:5], s[40:41]
	s_cbranch_execz .LBB0_442
	v_mov_b32_e32 v4, s3
	v_mov_b32_e32 v5, s11
	v_pk_add_f32 v[4:5], s[6:7], v[4:5]
	s_nop 0
	v_add_f32_e32 v4, v4, v5
	v_fmamk_f32 v4, v4, 0x3a800000, v172
	v_mul_f32_e32 v5, 0x4b800000, v4
	v_cmp_gt_f32_e32 vcc, s8, v4
	s_nop 1
	v_cndmask_b32_e32 v4, v4, v5, vcc
	v_rsq_f32_e32 v4, v4
	s_nop 0
	v_mul_f32_e32 v5, 0x45800000, v4
	v_cndmask_b32_e32 v4, v4, v5, vcc
	ds_write_b32 v0, v4 offset:4
; __device__ __forceinline__ void gmlp_unit(const TI ti, CArgs& a, int l, int u, unsigned char* ldsg) {
;     ...
;     for (int i = 0; i < 16; ++i) {
;         const int tok = w * 16 + i; const bf16_t* p = GV + (R0 + tok) * 1024 + lane * 16;
;         f32x4 x0, x1, x2, x3; unpack8(*(const u32x4*)p, x0, x1); unpack8(*(const u32x4*)(p + 8), x2, x3);
;         float ss = (x0.x * x0.x + x0.y * x0.y + x0.z * x0.z + x0.w * x0.w) + (x1.x * x1.x + x1.y * x1.y + x1.z * x1.z + x1.w * x1.w)
;                  + (x2.x * x2.x + x2.y * x2.y + x2.z * x2.z + x2.w * x2.w) + (x3.x * x3.x + x3.y * x3.y + x3.z * x3.z + x3.w * x3.w);
;         ss = wave_sum(ss);
;         if (lane == 0) rstd[tok] = rsqrtf(ss * (1.f / 1024.f) + 1e-6f);
;     }
.LBB0_442:
	s_or_b64 exec, exec, s[4:5]
	s_waitcnt vmcnt(2)
	v_mov_b32_e32 v4, v36
	v_mov_b32_e32 v5, v37
	v_mov_b32_e32 v6, v38
	v_mov_b32_e32 v7, v39
	v_mov_b32_e32 v8, v40
	v_mov_b32_e32 v9, v41
	v_mov_b32_e32 v10, v42
	v_mov_b32_e32 v11, v43
	v_lshlrev_b32_e32 v12, 16, v4
	v_and_b32_e32 v4, 0xffff0000, v4
	v_lshlrev_b32_e32 v14, 16, v6
	v_and_b32_e32 v6, 0xffff0000, v6
	v_lshlrev_b32_e32 v16, 16, v8
	v_and_b32_e32 v8, 0xffff0000, v8
	v_mul_f32_e32 v4, v4, v4
	v_mul_f32_e32 v6, v6, v6
	v_lshlrev_b32_e32 v13, 16, v5
	v_lshlrev_b32_e32 v15, 16, v7
	v_lshlrev_b32_e32 v18, 16, v10
	v_and_b32_e32 v10, 0xffff0000, v10
	v_mul_f32_e32 v8, v8, v8
	v_fmac_f32_e32 v4, v12, v12
	v_fmac_f32_e32 v6, v14, v14
	v_and_b32_e32 v5, 0xffff0000, v5
	v_and_b32_e32 v7, 0xffff0000, v7
	v_lshlrev_b32_e32 v17, 16, v9
	v_mul_f32_e32 v10, v10, v10
	v_fmac_f32_e32 v8, v16, v16
	v_fmac_f32_e32 v4, v13, v13
	v_fmac_f32_e32 v6, v15, v15
	v_and_b32_e32 v9, 0xffff0000, v9
	v_lshlrev_b32_e32 v19, 16, v11
	v_fmac_f32_e32 v10, v18, v18
	v_fmac_f32_e32 v8, v17, v17
	v_fmac_f32_e32 v4, v5, v5
	v_fmac_f32_e32 v6, v7, v7
	v_and_b32_e32 v11, 0xffff0000, v11
	v_fmac_f32_e32 v10, v19, v19
	v_fmac_f32_e32 v8, v9, v9
	v_add_f32_e32 v4, v4, v6
	v_fmac_f32_e32 v10, v11, v11
	v_add_f32_e32 v4, v4, v8
	v_add_f32_e32 v4, v10, v4
	s_nop 1
	v_add_f32_dpp v4, v4, v4 quad_perm:[1,0,3,2] row_mask:0xf bank_mask:0xf bound_ctrl:1
	s_nop 1
	v_add_f32_dpp v4, v4, v4 quad_perm:[2,3,0,1] row_mask:0xf bank_mask:0xf bound_ctrl:1
	s_nop 1
	v_add_f32_dpp v4, v4, v4 row_half_mirror row_mask:0xf bank_mask:0xf bound_ctrl:1
	s_nop 1
	v_add_f32_dpp v4, v4, v4 row_mirror row_mask:0xf bank_mask:0xf bound_ctrl:1
	s_nop 0
	v_readlane_b32 s6, v4, 0
	v_readlane_b32 s3, v4, 16
	v_readlane_b32 s7, v4, 32
	v_readlane_b32 s11, v4, 48
	s_and_saveexec_b64 s[4:5], s[40:41]
	s_cbranch_execz .LBB0_444
	v_mov_b32_e32 v4, s3
	v_mov_b32_e32 v5, s11
	v_pk_add_f32 v[4:5], s[6:7], v[4:5]
	s_nop 0
	v_add_f32_e32 v4, v4, v5
	v_fmamk_f32 v4, v4, 0x3a800000, v172
	v_mul_f32_e32 v5, 0x4b800000, v4
	v_cmp_gt_f32_e32 vcc, s8, v4
	s_nop 1
	v_cndmask_b32_e32 v4, v4, v5, vcc
	v_rsq_f32_e32 v4, v4
	s_nop 0
	v_mul_f32_e32 v5, 0x45800000, v4
	v_cndmask_b32_e32 v4, v4, v5, vcc
	ds_write_b32 v0, v4 offset:8
.LBB0_444:
	s_or_b64 exec, exec, s[4:5]
	s_waitcnt vmcnt(0)
	v_mov_b32_e32 v4, v44
	v_mov_b32_e32 v5, v45
	v_mov_b32_e32 v6, v46
	v_mov_b32_e32 v7, v47
	v_mov_b32_e32 v8, v48
	v_mov_b32_e32 v9, v49
	v_mov_b32_e32 v10, v50
	v_mov_b32_e32 v11, v51
	v_and_b32_e32 v3, 0xffff0000, v4
	v_lshlrev_b32_e32 v12, 16, v6
	v_and_b32_e32 v6, 0xffff0000, v6
	v_lshlrev_b32_e32 v2, 16, v4
	v_lshlrev_b32_e32 v14, 16, v8
	v_and_b32_e32 v8, 0xffff0000, v8
	v_mul_f32_e32 v3, v3, v3
	v_mul_f32_e32 v6, v6, v6
	v_lshlrev_b32_e32 v4, 16, v5
	v_lshlrev_b32_e32 v13, 16, v7
	v_lshlrev_b32_e32 v16, 16, v10
	v_and_b32_e32 v10, 0xffff0000, v10
	v_mul_f32_e32 v8, v8, v8
	v_fmac_f32_e32 v3, v2, v2
	v_fmac_f32_e32 v6, v12, v12
	v_and_b32_e32 v5, 0xffff0000, v5
	v_and_b32_e32 v7, 0xffff0000, v7
	v_lshlrev_b32_e32 v15, 16, v9
	v_mul_f32_e32 v10, v10, v10
	v_fmac_f32_e32 v8, v14, v14
	v_fmac_f32_e32 v3, v4, v4
	v_fmac_f32_e32 v6, v13, v13
	v_and_b32_e32 v9, 0xffff0000, v9
	v_lshlrev_b32_e32 v17, 16, v11
	v_fmac_f32_e32 v10, v16, v16
	v_fmac_f32_e32 v8, v15, v15
	v_fmac_f32_e32 v3, v5, v5
	v_fmac_f32_e32 v6, v7, v7
	v_and_b32_e32 v11, 0xffff0000, v11
	v_fmac_f32_e32 v10, v17, v17
	v_fmac_f32_e32 v8, v9, v9
	v_add_f32_e32 v2, v3, v6
	v_fmac_f32_e32 v10, v11, v11
	v_add_f32_e32 v2, v2, v8
	v_add_f32_e32 v2, v10, v2
	s_nop 1
	v_add_f32_dpp v2, v2, v2 quad_perm:[1,0,3,2] row_mask:0xf bank_mask:0xf bound_ctrl:1
	s_nop 1
	v_add_f32_dpp v2, v2, v2 quad_perm:[2,3,0,1] row_mask:0xf bank_mask:0xf bound_ctrl:1
	s_nop 1
	v_add_f32_dpp v2, v2, v2 row_half_mirror row_mask:0xf bank_mask:0xf bound_ctrl:1
	s_nop 1
	v_add_f32_dpp v2, v2, v2 row_mirror row_mask:0xf bank_mask:0xf bound_ctrl:1
	s_nop 0
	v_readlane_b32 s6, v2, 0
	v_readlane_b32 s3, v2, 16
	v_readlane_b32 s7, v2, 32
	v_readlane_b32 s11, v2, 48
	s_and_saveexec_b64 s[4:5], s[40:41]
	s_cbranch_execz .LBB0_437
	v_mov_b32_e32 v2, s3
	v_mov_b32_e32 v3, s11
	v_pk_add_f32 v[2:3], s[6:7], v[2:3]
	s_nop 0
	v_add_f32_e32 v2, v2, v3
	v_fmamk_f32 v2, v2, 0x3a800000, v172
	v_mul_f32_e32 v3, 0x4b800000, v2
	v_cmp_gt_f32_e32 vcc, s8, v2
	s_nop 1
	v_cndmask_b32_e32 v2, v2, v3, vcc
	v_rsq_f32_e32 v2, v2
	s_nop 0
	v_mul_f32_e32 v3, 0x45800000, v2
	v_cndmask_b32_e32 v2, v2, v3, vcc
	ds_write_b32 v0, v2 offset:12
	s_branch .LBB0_437

; __device__ __forceinline__ bf16_t f2bf(float f) { return (bf16_t)(pkbf(f, 0.f) & 0xffffu); }
; __device__ __forceinline__ void gmlp_unit(const TI ti, CArgs& a, int l, int u, unsigned char* ldsg) {
;     ...
;     for (int g = 0; g < 8; ++g) {
;         {
;             const int s = tid & 127, cc = tid >> 7; const float rs = rstd[s]; const bf16_t* p = GV + (R0 + s) * 1024 + g * 128 + cc * 32;
; #pragma unroll
;             for (int q = 0; q < 4; ++q) {
;                 f32x4 x0, x1; unpack8(*(const u32x4*)(p + 8 * q), x0, x1);
;                 const float* gp = gvg + g * 128 + cc * 32 + 8 * q; const int c0 = cc * 32 + 8 * q;
;                 VNT[(c0 + 0) * 136 + s] = f2bf(x0.x * rs * gp[0]); VNT[(c0 + 1) * 136 + s] = f2bf(x0.y * rs * gp[1]);
;                 VNT[(c0 + 2) * 136 + s] = f2bf(x0.z * rs * gp[2]); VNT[(c0 + 3) * 136 + s] = f2bf(x0.w * rs * gp[3]);
;                 VNT[(c0 + 4) * 136 + s] = f2bf(x1.x * rs * gp[4]); VNT[(c0 + 5) * 136 + s] = f2bf(x1.y * rs * gp[5]);
;                 VNT[(c0 + 6) * 136 + s] = f2bf(x1.z * rs * gp[6]); VNT[(c0 + 7) * 136 + s] = f2bf(x1.w * rs * gp[7]);
;             }
;         }
;         __syncthreads();
;     ...
;         const float* wrow = wsp + ((size_t)g * 128 + tt * 32 + r) * 128;
; #pragma unroll
;         for (int ks = 0; ks < 8; ++ks) {
;             const f32x4 a0 = *(const f32x4*)(wrow + 16 * ks + 8 * h), a1 = *(const f32x4*)(wrow + 16 * ks + 8 * h + 4);
.LBB0_447:
	global_load_dwordx4 v[90:93], v[144:145], off offset:-256
	global_load_dwordx4 v[94:97], v[144:145], off offset:-240
	global_load_dwordx4 v[98:101], v[144:145], off offset:-192
	global_load_dwordx4 v[162:165], v[144:145], off offset:-176
	global_load_dwordx4 v[198:201], v[144:145], off offset:-128
	global_load_dwordx4 v[202:205], v[144:145], off offset:-112
	global_load_dwordx4 v[206:209], v[144:145], off offset:-64
	global_load_dwordx4 v[210:213], v[144:145], off offset:-48
	v_lshl_add_u64 v[14:15], v[146:147], 0, s[42:43]
	ds_read_b32 v0, v156
	global_load_dwordx4 v[2:5], v[14:15], off offset:16
	global_load_dwordx4 v[6:9], v[14:15], off
	global_load_dwordx4 v[10:13], v[14:15], off offset:-16
	s_nop 0
	global_load_dwordx4 v[14:17], v[14:15], off offset:-32
	v_lshl_add_u64 v[30:31], v[102:103], 0, s[46:47]
	v_lshl_add_u64 v[150:151], v[130:131], 0, s[42:43]
	v_lshl_add_u64 v[154:155], v[134:135], 0, s[42:43]
	v_lshl_add_u64 v[168:169], v[138:139], 0, s[42:43]
	s_mov_b32 s3, 0x5e01000
	s_mov_b64 s[4:5], 0x10000
	v_lshl_add_u64 v[146:147], v[146:147], 0, s[24:25]
	v_lshl_add_u64 v[138:139], v[138:139], 0, s[24:25]
	v_lshl_add_u64 v[134:135], v[134:135], 0, s[24:25]
	v_lshl_add_u64 v[130:131], v[130:131], 0, s[24:25]
	s_waitcnt vmcnt(0)
	v_lshlrev_b32_e32 v18, 16, v14
	v_and_b32_e32 v32, 0xffff0000, v14
	v_lshlrev_b32_e32 v33, 16, v15
	v_and_b32_e32 v34, 0xffff0000, v15
	v_lshlrev_b32_e32 v35, 16, v16
	v_and_b32_e32 v36, 0xffff0000, v16
	v_lshlrev_b32_e32 v37, 16, v17
	v_and_b32_e32 v38, 0xffff0000, v17
	s_waitcnt lgkmcnt(0)
	v_mul_f32_e32 v39, v0, v18
	global_load_dwordx4 v[14:17], v[30:31], off offset:48
	global_load_dwordx4 v[18:21], v[30:31], off offset:32
	global_load_dwordx4 v[22:25], v[30:31], off offset:16
	global_load_dwordx4 v[26:29], v[30:31], off
	s_waitcnt vmcnt(0)
	v_mul_f32_e32 v26, v26, v39
	v_cvt_pk_bf16_f32 v26, v26, s0
	ds_write_b16 v158, v26 offset:512
	v_mul_f32_e32 v26, v0, v32
	v_mul_f32_e32 v26, v27, v26
	v_cvt_pk_bf16_f32 v26, v26, s0
	ds_write_b16 v159, v26 offset:784
	v_mul_f32_e32 v26, v0, v33
	v_mul_f32_e32 v26, v26, v28
	v_cvt_pk_bf16_f32 v26, v26, s0
	ds_write_b16 v159, v26 offset:1056
	v_mul_f32_e32 v26, v0, v34
	v_mul_f32_e32 v26, v26, v29
	v_cvt_pk_bf16_f32 v26, v26, s0
	ds_write_b16 v159, v26 offset:1328
	v_mul_f32_e32 v26, v0, v35
	v_mul_f32_e32 v22, v26, v22
	v_cvt_pk_bf16_f32 v22, v22, s0
	ds_write_b16 v159, v22 offset:1600
	v_mul_f32_e32 v22, v0, v36
	v_mul_f32_e32 v22, v22, v23
	v_cvt_pk_bf16_f32 v22, v22, s0
	ds_write_b16 v159, v22 offset:1872
	v_mul_f32_e32 v22, v0, v37
	v_mul_f32_e32 v22, v22, v24
	v_cvt_pk_bf16_f32 v22, v22, s0
	ds_write_b16 v159, v22 offset:2144
	v_mul_f32_e32 v22, v0, v38
	v_mul_f32_e32 v22, v22, v25
	v_cvt_pk_bf16_f32 v22, v22, s0
	ds_write_b16 v159, v22 offset:2416
	v_lshlrev_b32_e32 v22, 16, v10
	v_and_b32_e32 v10, 0xffff0000, v10
	v_mul_f32_e32 v22, v0, v22
	v_mul_f32_e32 v10, v0, v10
	v_mul_f32_e32 v18, v18, v22
	v_mul_f32_e32 v10, v19, v10
	v_lshlrev_b32_e32 v23, 16, v11
	v_cvt_pk_bf16_f32 v18, v18, s0
	v_cvt_pk_bf16_f32 v10, v10, s0
	ds_write_b16 v158, v18 offset:2688
	ds_write_b16 v159, v10 offset:2960
	v_mul_f32_e32 v10, v0, v23
	v_mul_f32_e32 v10, v10, v20
	v_and_b32_e32 v11, 0xffff0000, v11
	v_cvt_pk_bf16_f32 v10, v10, s0
	ds_write_b16 v159, v10 offset:3232
	v_mul_f32_e32 v10, v0, v11
	v_mul_f32_e32 v10, v10, v21
	v_lshlrev_b32_e32 v24, 16, v12
	v_cvt_pk_bf16_f32 v10, v10, s0
	ds_write_b16 v159, v10 offset:3504
	v_mul_f32_e32 v10, v0, v24
	v_mul_f32_e32 v10, v10, v14
	v_and_b32_e32 v12, 0xffff0000, v12
	v_cvt_pk_bf16_f32 v10, v10, s0
	ds_write_b16 v159, v10 offset:3776
	v_mul_f32_e32 v10, v0, v12
	v_mul_f32_e32 v10, v10, v15
	v_lshlrev_b32_e32 v25, 16, v13
	v_cvt_pk_bf16_f32 v10, v10, s0
	ds_write_b16 v159, v10 offset:4048
	v_mul_f32_e32 v10, v0, v25
	v_mul_f32_e32 v10, v10, v16
	v_and_b32_e32 v13, 0xffff0000, v13
	v_cvt_pk_bf16_f32 v10, v10, s0
	ds_write_b16 v159, v10 offset:4320
	v_mul_f32_e32 v10, v0, v13
	v_mul_f32_e32 v10, v10, v17
	v_cvt_pk_bf16_f32 v10, v10, s0
	ds_write_b16 v159, v10 offset:4592
	v_lshlrev_b32_e32 v10, 16, v6
	v_and_b32_e32 v22, 0xffff0000, v6
	v_lshlrev_b32_e32 v23, 16, v7
	v_and_b32_e32 v24, 0xffff0000, v7
	v_lshlrev_b32_e32 v25, 16, v8
	v_and_b32_e32 v26, 0xffff0000, v8
	v_lshlrev_b32_e32 v27, 16, v9
	v_and_b32_e32 v28, 0xffff0000, v9
	v_mul_f32_e32 v29, v0, v10
	global_load_dwordx4 v[6:9], v[30:31], off offset:112
	global_load_dwordx4 v[10:13], v[30:31], off offset:96
	global_load_dwordx4 v[14:17], v[30:31], off offset:80
	global_load_dwordx4 v[18:21], v[30:31], off offset:64
	s_waitcnt vmcnt(0)
	v_mul_f32_e32 v18, v18, v29
	v_cvt_pk_bf16_f32 v18, v18, s0
	ds_write_b16 v158, v18 offset:4864
	v_mul_f32_e32 v18, v0, v22
	v_mul_f32_e32 v18, v19, v18
	v_cvt_pk_bf16_f32 v18, v18, s0
	ds_write_b16 v159, v18 offset:5136
	v_mul_f32_e32 v18, v0, v23
	v_mul_f32_e32 v18, v18, v20
	v_cvt_pk_bf16_f32 v18, v18, s0
	ds_write_b16 v159, v18 offset:5408
	v_mul_f32_e32 v18, v0, v24
	v_mul_f32_e32 v18, v18, v21
	v_cvt_pk_bf16_f32 v18, v18, s0
	ds_write_b16 v159, v18 offset:5680
	v_mul_f32_e32 v18, v0, v25
	v_mul_f32_e32 v14, v18, v14
	v_cvt_pk_bf16_f32 v14, v14, s0
	ds_write_b16 v159, v14 offset:5952
	v_mul_f32_e32 v14, v0, v26
	v_mul_f32_e32 v14, v14, v15
	v_cvt_pk_bf16_f32 v14, v14, s0
	ds_write_b16 v159, v14 offset:6224
	v_mul_f32_e32 v14, v0, v27
	v_mul_f32_e32 v14, v14, v16
	v_cvt_pk_bf16_f32 v14, v14, s0
	ds_write_b16 v159, v14 offset:6496
	v_mul_f32_e32 v14, v0, v28
	v_mul_f32_e32 v14, v14, v17
	v_cvt_pk_bf16_f32 v14, v14, s0
	ds_write_b16 v159, v14 offset:6768
	v_lshlrev_b32_e32 v14, 16, v2
	v_and_b32_e32 v2, 0xffff0000, v2
	v_mul_f32_e32 v14, v0, v14
	v_mul_f32_e32 v2, v0, v2
	v_mul_f32_e32 v10, v10, v14
	v_mul_f32_e32 v2, v11, v2
	v_lshlrev_b32_e32 v15, 16, v3
	v_cvt_pk_bf16_f32 v10, v10, s0
	v_cvt_pk_bf16_f32 v2, v2, s0
	ds_write_b16 v158, v10 offset:7040
	ds_write_b16 v159, v2 offset:7312
	v_mul_f32_e32 v2, v0, v15
	v_mul_f32_e32 v2, v2, v12
	v_and_b32_e32 v3, 0xffff0000, v3
	v_cvt_pk_bf16_f32 v2, v2, s0
	ds_write_b16 v159, v2 offset:7584
	v_mul_f32_e32 v2, v0, v3
	v_mul_f32_e32 v2, v2, v13
	v_lshlrev_b32_e32 v16, 16, v4
	v_cvt_pk_bf16_f32 v2, v2, s0
	ds_write_b16 v159, v2 offset:7856
	v_mul_f32_e32 v2, v0, v16
	v_mul_f32_e32 v2, v2, v6
	v_and_b32_e32 v4, 0xffff0000, v4
	v_cvt_pk_bf16_f32 v2, v2, s0
	ds_write_b16 v159, v2 offset:8128
	v_mul_f32_e32 v2, v0, v4
	v_mul_f32_e32 v2, v2, v7
	v_lshlrev_b32_e32 v17, 16, v5
	v_and_b32_e32 v5, 0xffff0000, v5
	v_cvt_pk_bf16_f32 v2, v2, s0
	ds_write_b16 v159, v2 offset:8400
	v_mul_f32_e32 v2, v0, v17
	v_mul_f32_e32 v0, v0, v5
	v_mul_f32_e32 v2, v2, v8
	v_mul_f32_e32 v0, v0, v9
	v_cvt_pk_bf16_f32 v2, v2, s0
	v_cvt_pk_bf16_f32 v0, v0, s0
	ds_write_b16 v159, v2 offset:8672
	ds_write_b16 v159, v0 offset:8944
	s_waitcnt lgkmcnt(0)
	s_barrier
; #define MFMA32(a, b, c) __builtin_amdgcn_mfma_f32_32x32x16_bf16((a), (b), (c), 0, 0, 0)
; __device__ __forceinline__ float bf2f(unsigned v) { return __uint_as_float(v << 16); }
; __device__ __forceinline__ u32x4 pack8(f32x4 v0, f32x4 v1) { u32x4 o; o.x = pkbf(v0.x, v0.y); o.y = pkbf(v0.z, v0.w); o.z = pkbf(v1.x, v1.y); o.w = pkbf(v1.z, v1.w); return o; }
; __device__ __forceinline__ void gmlp_unit(const TI ti, CArgs& a, int l, int u, unsigned char* ldsg) {
;     ...
;         f32x16 acc0, acc1;
; #pragma unroll
;         for (int i = 0; i < 16; ++i) { acc0[i] = 0.f; acc1[i] = 0.f; }
;         const float* wrow = wsp + ((size_t)g * 128 + tt * 32 + r) * 128;
; #pragma unroll
;         for (int ks = 0; ks < 8; ++ks) {
;             const f32x4 a0 = *(const f32x4*)(wrow + 16 * ks + 8 * h), a1 = *(const f32x4*)(wrow + 16 * ks + 8 * h + 4);
;             const bf16x8 af = __builtin_bit_cast(bf16x8, pack8(a0, a1));
;             const bf16x8 b0 = *(const bf16x8*)(VNT + (chh * 64 + r) * 136 + 16 * ks + 8 * h);
;             const bf16x8 b1 = *(const bf16x8*)(VNT + (chh * 64 + 32 + r) * 136 + 16 * ks + 8 * h);
;             acc0 = MFMA32(af, b0, acc0); acc1 = MFMA32(af, b1, acc1);
;         }
;         {
;             const bf16_t* GUr = GU; float uu0[16], uu1[16], bb[16];
; #pragma unroll
;             for (int reg = 0; reg < 16; ++reg) {
;                 const int t = tt * 32 + (reg & 3) + 8 * (reg >> 2) + 4 * h; const size_t i0 = (R0 + t) * 1024 + g * 128 + chh * 64 + r;
;                 bb[reg] = bsp[g * 128 + t]; uu0[reg] = bf2f(GUr[i0]); uu1[reg] = bf2f(GUr[i0 + 32]);
;             }
;             asm volatile("" ::: "memory");
	v_cvt_pk_bf16_f32 v18, v90, v91
	v_cvt_pk_bf16_f32 v19, v92, v93
	v_cvt_pk_bf16_f32 v20, v94, v95
	v_cvt_pk_bf16_f32 v21, v96, v97
	v_cvt_pk_bf16_f32 v34, v98, v99
	v_cvt_pk_bf16_f32 v35, v100, v101
	v_cvt_pk_bf16_f32 v36, v162, v163
	v_cvt_pk_bf16_f32 v37, v164, v165
	v_cvt_pk_bf16_f32 v42, v198, v199
	v_cvt_pk_bf16_f32 v43, v200, v201
	v_cvt_pk_bf16_f32 v44, v202, v203
	v_cvt_pk_bf16_f32 v45, v204, v205
	v_cvt_pk_bf16_f32 v50, v206, v207
	v_cvt_pk_bf16_f32 v51, v208, v209
	v_cvt_pk_bf16_f32 v52, v210, v211
	v_cvt_pk_bf16_f32 v53, v212, v213
	global_load_dwordx4 v[90:93], v[144:145], off offset:0
	global_load_dwordx4 v[94:97], v[144:145], off offset:16
	global_load_dwordx4 v[98:101], v[144:145], off offset:64
	global_load_dwordx4 v[162:165], v[144:145], off offset:80
	global_load_dwordx4 v[198:201], v[144:145], off offset:128
	global_load_dwordx4 v[202:205], v[144:145], off offset:144
	global_load_dwordx4 v[206:209], v[144:145], off offset:192
	global_load_dwordx4 v[210:213], v[144:145], off offset:208
	v_lshl_add_u64 v[144:145], v[144:145], 0, s[4:5]
	ds_read_b128 v[26:29], v157 offset:512
	ds_read_b128 v[30:33], v157 offset:544
	ds_read_b128 v[174:177], v157 offset:576
	ds_read_b128 v[214:217], v157 offset:608
	ds_read_b128 v[22:25], v157 offset:9216
	ds_read_b128 v[38:41], v157 offset:9248
	ds_read_b128 v[46:49], v157 offset:9280
	ds_read_b128 v[54:57], v157 offset:9312
	s_waitcnt lgkmcnt(7)
	v_mfma_f32_32x32x16_bf16 v[2:17], v[18:21], v[26:29], 0
	s_waitcnt lgkmcnt(6)
	v_mfma_f32_32x32x16_bf16 v[2:17], v[34:37], v[30:33], v[2:17]
	ds_read_b128 v[26:29], v157 offset:640
	ds_read_b128 v[30:33], v157 offset:672
	s_waitcnt lgkmcnt(7)
	v_mfma_f32_32x32x16_bf16 v[2:17], v[42:45], v[174:177], v[2:17]
	s_waitcnt lgkmcnt(6)
	v_mfma_f32_32x32x16_bf16 v[2:17], v[50:53], v[214:217], v[2:17]
	ds_read_b128 v[174:177], v157 offset:704
	ds_read_b128 v[214:217], v157 offset:736
	ds_read_b128 v[62:65], v157 offset:9344
	ds_read_b128 v[70:73], v157 offset:9376
	ds_read_b128 v[78:81], v157 offset:9408
	ds_read_b128 v[86:89], v157 offset:9440
	s_waitcnt vmcnt(0)
	v_cvt_pk_bf16_f32 v58, v90, v91
	v_cvt_pk_bf16_f32 v59, v92, v93
	v_cvt_pk_bf16_f32 v60, v94, v95
	v_cvt_pk_bf16_f32 v61, v96, v97
	v_cvt_pk_bf16_f32 v66, v98, v99
	v_cvt_pk_bf16_f32 v67, v100, v101
	v_cvt_pk_bf16_f32 v68, v162, v163
	v_cvt_pk_bf16_f32 v69, v164, v165
	v_cvt_pk_bf16_f32 v74, v198, v199
	v_cvt_pk_bf16_f32 v75, v200, v201
	v_cvt_pk_bf16_f32 v76, v202, v203
	v_cvt_pk_bf16_f32 v77, v204, v205
	v_cvt_pk_bf16_f32 v82, v206, v207
	v_cvt_pk_bf16_f32 v83, v208, v209
	v_cvt_pk_bf16_f32 v84, v210, v211
	v_cvt_pk_bf16_f32 v85, v212, v213
	s_waitcnt lgkmcnt(7)
	v_mfma_f32_32x32x16_bf16 v[2:17], v[58:61], v[26:29], v[2:17]
	s_waitcnt lgkmcnt(6)
	v_mfma_f32_32x32x16_bf16 v[2:17], v[66:69], v[30:33], v[2:17]
	s_waitcnt lgkmcnt(5)
	v_mfma_f32_32x32x16_bf16 v[2:17], v[74:77], v[174:177], v[2:17]
	s_waitcnt lgkmcnt(4)
	v_mfma_f32_32x32x16_bf16 v[2:17], v[82:85], v[214:217], v[2:17]
	s_waitcnt lgkmcnt(0)
	v_lshl_add_u64 v[28:29], v[128:129], 0, s[42:43]
	v_add_co_u32_e32 v148, vcc, s82, v28
	v_lshl_add_u64 v[26:27], v[110:111], 0, s[46:47]
	s_nop 0
	v_addc_co_u32_e32 v149, vcc, 0, v29, vcc
	global_load_dwordx4 v[90:93], v[26:27], off
	global_load_dwordx4 v[94:97], v[26:27], off offset:32
	global_load_dwordx4 v[98:101], v[26:27], off offset:64
	global_load_dwordx4 v[162:165], v[26:27], off offset:96
	global_load_ushort v0, v[148:149], off
	global_load_ushort v161, v[148:149], off offset:64
	global_load_ushort v174, v[148:149], off offset:2048
	global_load_ushort v175, v[148:149], off offset:2112
	global_load_ushort v176, v[150:151], off offset:-64
	global_load_ushort v177, v[150:151], off
	global_load_ushort v179, v[150:151], off offset:1984
	global_load_ushort v181, v[150:151], off offset:2048
	v_lshl_add_u64 v[28:29], v[132:133], 0, s[42:43]
	v_add_co_u32_e32 v152, vcc, s82, v28
	v_lshl_add_u64 v[132:133], v[132:133], 0, s[24:25]
	s_nop 0
	v_addc_co_u32_e32 v153, vcc, 0, v29, vcc
	global_load_ushort v197, v[152:153], off
	global_load_ushort v198, v[152:153], off offset:64
	global_load_ushort v199, v[152:153], off offset:2048
	global_load_ushort v200, v[152:153], off offset:2112
	global_load_ushort v201, v[154:155], off offset:-64
	global_load_ushort v202, v[154:155], off
	global_load_ushort v203, v[154:155], off offset:1984
	global_load_ushort v204, v[154:155], off offset:2048
	v_lshl_add_u64 v[28:29], v[136:137], 0, s[42:43]
	v_add_co_u32_e32 v166, vcc, s82, v28
	v_lshl_add_u64 v[136:137], v[136:137], 0, s[24:25]
	s_nop 0
	v_addc_co_u32_e32 v167, vcc, 0, v29, vcc
	global_load_ushort v205, v[166:167], off
	global_load_ushort v206, v[166:167], off offset:64
	global_load_ushort v207, v[166:167], off offset:2048
	global_load_ushort v208, v[166:167], off offset:2112
	v_lshl_add_u64 v[26:27], v[140:141], 0, s[42:43]
	v_add_co_u32_e32 v170, vcc, s82, v26
	v_lshl_add_u64 v[140:141], v[140:141], 0, s[24:25]
	s_nop 0
	v_addc_co_u32_e32 v171, vcc, 0, v27, vcc
	global_load_ushort v213, v[170:171], off
	global_load_ushort v214, v[170:171], off offset:64
	v_lshl_add_u64 v[26:27], v[142:143], 0, s[42:43]
	v_add_co_u32_e32 v182, vcc, s82, v26
	v_lshl_add_u64 v[142:143], v[142:143], 0, s[24:25]
	s_nop 0
	v_addc_co_u32_e32 v183, vcc, 0, v27, vcc
	v_add_co_u32_e32 v184, vcc, s3, v26
	s_nop 1
	v_addc_co_u32_e32 v185, vcc, 0, v27, vcc
	global_load_ushort v209, v[168:169], off offset:-64
	global_load_ushort v210, v[168:169], off
	global_load_ushort v211, v[168:169], off offset:1984
	global_load_ushort v212, v[168:169], off offset:2048
	global_load_ushort v217, v[184:185], off
	global_load_ushort v218, v[184:185], off offset:64
	global_load_ushort v219, v[184:185], off offset:2048
	global_load_ushort v220, v[184:185], off offset:2112
	global_load_ushort v215, v[182:183], off offset:2048
	global_load_ushort v216, v[182:183], off offset:2112
	v_lshl_add_u64 v[128:129], v[128:129], 0, s[24:25]
	s_add_u32 s46, s46, 0x200
	s_addc_u32 s47, s47, 0
	s_cmpk_lg_i32 s46, 0x1000
	s_waitcnt vmcnt(0)
; __device__ __forceinline__ float bf2f(unsigned v) { return __uint_as_float(v << 16); }
; __device__ __forceinline__ bf16_t f2bf(float f) { return (bf16_t)(pkbf(f, 0.f) & 0xffffu); }
; __device__ __forceinline__ void gmlp_unit(const TI ti, CArgs& a, int l, int u, unsigned char* ldsg) {
;     ...
;         {
;             const bf16_t* GUr = GU; float uu0[16], uu1[16], bb[16];
; #pragma unroll
;             for (int reg = 0; reg < 16; ++reg) {
;                 const int t = tt * 32 + (reg & 3) + 8 * (reg >> 2) + 4 * h; const size_t i0 = (R0 + t) * 1024 + g * 128 + chh * 64 + r;
;                 bb[reg] = bsp[g * 128 + t]; uu0[reg] = bf2f(GUr[i0]); uu1[reg] = bf2f(GUr[i0 + 32]);
;             }
;             asm volatile("" ::: "memory");
; #pragma unroll
;             for (int reg = 0; reg < 16; ++reg) {
;                 const int t = tt * 32 + (reg & 3) + 8 * (reg >> 2) + 4 * h; const size_t i0 = (R0 + t) * 1024 + g * 128 + chh * 64 + r;
;                 GU[i0] = f2bf(uu0[reg] * (acc0[reg] + bb[reg])); GU[i0 + 32] = f2bf(uu1[reg] * (acc1[reg] + bb[reg]));
;             }
;         }
;         __syncthreads();
;     }
	v_lshlrev_b32_e32 v0, 16, v0
	v_lshlrev_b32_e32 v161, 16, v161
	v_lshlrev_b32_e32 v174, 16, v174
	v_lshlrev_b32_e32 v175, 16, v175
	v_lshlrev_b32_e32 v176, 16, v176
	v_lshlrev_b32_e32 v177, 16, v177
	v_lshlrev_b32_e32 v179, 16, v179
	v_lshlrev_b32_e32 v181, 16, v181
	v_lshlrev_b32_e32 v197, 16, v197
	v_lshlrev_b32_e32 v198, 16, v198
	v_lshlrev_b32_e32 v199, 16, v199
	v_lshlrev_b32_e32 v200, 16, v200
	v_lshlrev_b32_e32 v201, 16, v201
	v_lshlrev_b32_e32 v202, 16, v202
	v_lshlrev_b32_e32 v203, 16, v203
	v_lshlrev_b32_e32 v204, 16, v204
	v_lshlrev_b32_e32 v205, 16, v205
	v_lshlrev_b32_e32 v206, 16, v206
	v_lshlrev_b32_e32 v207, 16, v207
	v_lshlrev_b32_e32 v208, 16, v208
	v_lshlrev_b32_e32 v209, 16, v209
	v_lshlrev_b32_e32 v210, 16, v210
	v_lshlrev_b32_e32 v211, 16, v211
	v_lshlrev_b32_e32 v212, 16, v212
	v_lshlrev_b32_e32 v213, 16, v213
	v_lshlrev_b32_e32 v214, 16, v214
	v_lshlrev_b32_e32 v215, 16, v215
	v_lshlrev_b32_e32 v216, 16, v216
	v_lshlrev_b32_e32 v217, 16, v217
	v_lshlrev_b32_e32 v218, 16, v218
	v_lshlrev_b32_e32 v219, 16, v219
	v_lshlrev_b32_e32 v220, 16, v220
	v_add_f32_e32 v2, v2, v90
	v_mul_f32_e32 v0, v2, v0
	v_cvt_pk_bf16_f32 v0, v0, s0
	global_store_short v[148:149], v0, off
	v_mfma_f32_32x32x16_bf16 v[18:33], v[18:21], v[22:25], 0
	v_mfma_f32_32x32x16_bf16 v[18:33], v[34:37], v[38:41], v[18:33]
	v_mfma_f32_32x32x16_bf16 v[18:33], v[42:45], v[46:49], v[18:33]
	v_mfma_f32_32x32x16_bf16 v[18:33], v[50:53], v[54:57], v[18:33]
	v_mfma_f32_32x32x16_bf16 v[18:33], v[58:61], v[62:65], v[18:33]
	v_mfma_f32_32x32x16_bf16 v[18:33], v[66:69], v[70:73], v[18:33]
	v_mfma_f32_32x32x16_bf16 v[18:33], v[74:77], v[78:81], v[18:33]
	s_waitcnt lgkmcnt(0)
	v_mfma_f32_32x32x16_bf16 v[18:33], v[82:85], v[86:89], v[18:33]
	s_nop 11
	v_add_f32_e32 v0, v90, v18
	v_mul_f32_e32 v0, v0, v161
	v_cvt_pk_bf16_f32 v0, v0, s0
	global_store_short v[148:149], v0, off offset:64
	v_add_f32_e32 v0, v3, v91
	v_mul_f32_e32 v0, v0, v174
	v_cvt_pk_bf16_f32 v0, v0, s0
	global_store_short v[148:149], v0, off offset:2048
	v_add_f32_e32 v0, v91, v19
	v_mul_f32_e32 v0, v0, v175
	v_cvt_pk_bf16_f32 v0, v0, s0
	global_store_short v[148:149], v0, off offset:2112
	v_add_f32_e32 v0, v4, v92
	v_mul_f32_e32 v0, v0, v176
	v_cvt_pk_bf16_f32 v0, v0, s0
	global_store_short v[150:151], v0, off offset:-64
	v_add_f32_e32 v0, v92, v20
	v_mul_f32_e32 v0, v0, v177
	v_cvt_pk_bf16_f32 v0, v0, s0
	global_store_short v[150:151], v0, off
	v_add_f32_e32 v0, v5, v93
	v_mul_f32_e32 v0, v0, v179
	v_cvt_pk_bf16_f32 v0, v0, s0
	global_store_short v[150:151], v0, off offset:1984
	v_add_f32_e32 v0, v93, v21
	v_mul_f32_e32 v0, v0, v181
	v_cvt_pk_bf16_f32 v0, v0, s0
	global_store_short v[150:151], v0, off offset:2048
	v_add_f32_e32 v0, v6, v94
	v_mul_f32_e32 v0, v0, v197
	v_cvt_pk_bf16_f32 v0, v0, s0
	global_store_short v[152:153], v0, off
	v_add_f32_e32 v0, v94, v22
	v_mul_f32_e32 v0, v0, v198
	v_cvt_pk_bf16_f32 v0, v0, s0
	global_store_short v[152:153], v0, off offset:64
	v_add_f32_e32 v0, v7, v95
	v_mul_f32_e32 v0, v0, v199
	v_cvt_pk_bf16_f32 v0, v0, s0
	global_store_short v[152:153], v0, off offset:2048
	v_add_f32_e32 v0, v95, v23
	v_mul_f32_e32 v0, v0, v200
	v_cvt_pk_bf16_f32 v0, v0, s0
	global_store_short v[152:153], v0, off offset:2112
	v_add_f32_e32 v0, v8, v96
	v_mul_f32_e32 v0, v0, v201
	v_cvt_pk_bf16_f32 v0, v0, s0
	global_store_short v[154:155], v0, off offset:-64
	v_add_f32_e32 v0, v96, v24
	v_mul_f32_e32 v0, v0, v202
	v_cvt_pk_bf16_f32 v0, v0, s0
	global_store_short v[154:155], v0, off
	v_add_f32_e32 v0, v9, v97
	v_mul_f32_e32 v0, v0, v203
	v_cvt_pk_bf16_f32 v0, v0, s0
	global_store_short v[154:155], v0, off offset:1984
	v_add_f32_e32 v0, v97, v25
	v_mul_f32_e32 v0, v0, v204
	v_cvt_pk_bf16_f32 v0, v0, s0
	global_store_short v[154:155], v0, off offset:2048
	v_add_f32_e32 v0, v10, v98
	v_mul_f32_e32 v0, v0, v205
	v_cvt_pk_bf16_f32 v0, v0, s0
	global_store_short v[166:167], v0, off
	v_add_f32_e32 v0, v98, v26
	v_mul_f32_e32 v0, v0, v206
	v_cvt_pk_bf16_f32 v0, v0, s0
	global_store_short v[166:167], v0, off offset:64
	v_add_f32_e32 v0, v11, v99
	v_mul_f32_e32 v0, v0, v207
	v_cvt_pk_bf16_f32 v0, v0, s0
	global_store_short v[166:167], v0, off offset:2048
	v_add_f32_e32 v0, v99, v27
	v_mul_f32_e32 v0, v0, v208
	v_cvt_pk_bf16_f32 v0, v0, s0
	global_store_short v[166:167], v0, off offset:2112
	v_add_f32_e32 v0, v12, v100
	v_mul_f32_e32 v0, v0, v209
	v_cvt_pk_bf16_f32 v0, v0, s0
	global_store_short v[168:169], v0, off offset:-64
	v_add_f32_e32 v0, v100, v28
	v_mul_f32_e32 v0, v0, v210
	v_cvt_pk_bf16_f32 v0, v0, s0
	global_store_short v[168:169], v0, off
	v_add_f32_e32 v0, v13, v101
	v_mul_f32_e32 v0, v0, v211
	v_cvt_pk_bf16_f32 v0, v0, s0
	global_store_short v[168:169], v0, off offset:1984
	v_add_f32_e32 v0, v101, v29
	v_mul_f32_e32 v0, v0, v212
	v_cvt_pk_bf16_f32 v0, v0, s0
	global_store_short v[168:169], v0, off offset:2048
	v_add_f32_e32 v0, v14, v162
	v_mul_f32_e32 v0, v0, v213
	v_cvt_pk_bf16_f32 v0, v0, s0
	global_store_short v[170:171], v0, off
	v_add_f32_e32 v0, v162, v30
	v_mul_f32_e32 v0, v0, v214
	v_cvt_pk_bf16_f32 v0, v0, s0
	global_store_short v[170:171], v0, off offset:64
	v_add_f32_e32 v0, v15, v163
	v_mul_f32_e32 v0, v0, v215
	v_cvt_pk_bf16_f32 v0, v0, s0
	global_store_short v[182:183], v0, off offset:2048
	v_add_f32_e32 v0, v163, v31
	v_mul_f32_e32 v0, v0, v216
	v_cvt_pk_bf16_f32 v0, v0, s0
	global_store_short v[182:183], v0, off offset:2112
	v_add_f32_e32 v0, v16, v164
	v_mul_f32_e32 v0, v0, v217
	v_cvt_pk_bf16_f32 v0, v0, s0
	global_store_short v[184:185], v0, off
	v_add_f32_e32 v0, v164, v32
	v_mul_f32_e32 v0, v0, v218
	v_cvt_pk_bf16_f32 v0, v0, s0
	global_store_short v[184:185], v0, off offset:64
	v_add_f32_e32 v0, v17, v165
	v_mul_f32_e32 v0, v0, v219
	v_cvt_pk_bf16_f32 v0, v0, s0
	global_store_short v[184:185], v0, off offset:2048
	v_add_f32_e32 v0, v165, v33
	v_mul_f32_e32 v0, v0, v220
	v_cvt_pk_bf16_f32 v0, v0, s0
	global_store_short v[184:185], v0, off offset:2112
	s_barrier
	s_cbranch_scc1 .LBB0_447
	s_add_i32 s1, s1, s0
	v_lshl_add_u64 v[104:105], v[104:105], 0, s[44:45]
	v_lshl_add_u64 v[106:107], v[106:107], 0, s[44:45]
	v_lshl_add_u64 v[112:113], v[112:113], 0, s[44:45]
	v_lshl_add_u64 v[114:115], v[114:115], 0, s[44:45]
	v_lshl_add_u64 v[116:117], v[116:117], 0, s[44:45]
	v_lshl_add_u64 v[118:119], v[118:119], 0, s[44:45]
	v_lshl_add_u64 v[120:121], v[120:121], 0, s[44:45]
	v_lshl_add_u64 v[122:123], v[122:123], 0, s[44:45]
	v_lshl_add_u64 v[124:125], v[124:125], 0, s[44:45]
	s_cmp_ge_i32 s1, s10
	v_lshl_add_u64 v[126:127], v[126:127], 0, s[44:45]
	s_cbranch_scc0 .LBB0_436
